# gla_g1m: next item's V/K/Q/gate-logit rows prefetched into spare VGPRs ~1us before the current item ends; item top consumes them with moves
# baseline (speedup 1.0000x reference)
.LBB0_212:
	s_and_b64 vcc, exec, s[0:1]
	s_cbranch_vccz .LBB0_350
	s_cmp_gt_i32 s66, 0
	s_mov_b64 s[0:1], -1
	s_cbranch_scc0 .LBB0_240
	s_cmp_gt_i32 s66, 1
	s_cbranch_scc0 .LBB0_353
	v_ashrrev_i32_e32 v142, 4, v154
	v_lshlrev_b32_e32 v0, 2, v142
	v_and_b32_e32 v140, 15, v154
	v_add_u32_e32 v155, 0x200, v154
	v_and_b32_e32 v0, 12, v0
	v_bfe_u32 v4, v142, 2, 2
	v_ashrrev_i32_e32 v143, 4, v155
	v_bitop3_b32 v0, v0, v140, v4 bitop3:0x36
	v_lshlrev_b32_e32 v145, 4, v0
	v_lshlrev_b32_e32 v0, 2, v143
	v_and_b32_e32 v0, 12, v0
	v_bfe_u32 v4, v143, 2, 2
	s_waitcnt lgkmcnt(0)
	v_ashrrev_i32_e32 v3, 6, v154
	v_lshlrev_b32_e32 v2, 3, v154
	v_bitop3_b32 v0, v0, v140, v4 bitop3:0x36
	v_lshrrev_b32_e32 v5, 3, v154
	s_cmpk_lt_i32 s84, 0x820
	s_waitcnt vmcnt(0)
	v_and_b32_e32 v39, 3, v154
	v_lshlrev_b32_e32 v141, 2, v154
	v_and_b32_e32 v36, 8, v2
	v_lshlrev_b32_e32 v144, 8, v142
	v_lshlrev_b32_e32 v146, 8, v143
	v_lshlrev_b32_e32 v147, 4, v0
	v_and_b32_e32 v37, 12, v154
	v_readfirstlane_b32 s6, v3
	v_and_b32_e32 v38, 2, v5
	s_cbranch_scc0 .LBB0_254
	v_readlane_b32 s26, v254, 58
	v_ashrrev_i32_e32 v42, 3, v154
	v_and_b32_e32 v6, 28, v141
	v_readlane_b32 s27, v254, 59
	v_lshlrev_b32_e32 v11, 7, v42
	v_lshlrev_b32_e32 v12, 2, v6
	v_readlane_b32 s18, v253, 53
	s_and_b64 s[2:3], s[26:27], exec
	v_and_b32_e32 v7, 63, v154
	v_add3_u32 v43, s18, v11, v12
	v_lshrrev_b32_e32 v11, 6, v154
	v_bfe_u32 v13, v154, 6, 2
	s_cselect_b32 s2, 0, 0x100
	v_or_b32_e32 v44, s2, v7
	v_lshlrev_b32_e32 v16, 4, v13
	v_lshlrev_b32_e32 v11, 4, v11
	s_movk_i32 s2, 0xff
	v_ashrrev_i32_e32 v12, 8, v154
	v_cmp_lt_u32_e64 s[36:37], s2, v154
	v_or_b32_e32 v18, 14, v16
	v_or_b32_e32 v19, 1, v11
	v_lshlrev_b32_e32 v0, 2, v7
	v_lshlrev_b32_e32 v7, 6, v12
	v_cndmask_b32_e64 v18, v19, v18, s[36:37]
	v_add_u32_e32 v14, s18, v7
	s_movk_i32 s18, 0x110
	v_lshlrev_b32_e32 v33, 7, v18
	v_add_u32_e32 v18, v18, v7
	v_mul_lo_u32 v34, v18, s18
	v_or_b32_e32 v18, 13, v16
	v_or_b32_e32 v19, 2, v11
	v_cndmask_b32_e64 v18, v19, v18, s[36:37]
	v_lshlrev_b32_e32 v35, 7, v18
	v_add_u32_e32 v18, v18, v7
	v_mul_lo_u32 v55, v18, s18
	v_or_b32_e32 v18, 12, v16
	v_or_b32_e32 v19, 3, v11
	v_cndmask_b32_e64 v18, v19, v18, s[36:37]
	v_lshlrev_b32_e32 v56, 7, v18
	v_add_u32_e32 v18, v18, v7
	v_mul_lo_u32 v57, v18, s18
	v_or_b32_e32 v18, 11, v16
	v_or_b32_e32 v19, 4, v11
	v_cndmask_b32_e64 v18, v19, v18, s[36:37]
	v_lshlrev_b32_e32 v58, 7, v18
	v_add_u32_e32 v18, v18, v7
	v_mul_lo_u32 v59, v18, s18
	v_or_b32_e32 v18, 10, v16
	v_or_b32_e32 v19, 5, v11
	v_cndmask_b32_e64 v18, v19, v18, s[36:37]
	v_lshlrev_b32_e32 v60, 7, v18
	v_add_u32_e32 v18, v18, v7
	v_mul_lo_u32 v61, v18, s18
	v_or_b32_e32 v18, 9, v16
	v_or_b32_e32 v19, 6, v11
	v_cndmask_b32_e64 v18, v19, v18, s[36:37]
	v_lshlrev_b32_e32 v62, 7, v18
	v_add_u32_e32 v18, v18, v7
	v_mul_lo_u32 v63, v18, s18
	v_or_b32_e32 v18, 8, v16
	v_or_b32_e32 v19, 7, v11
	v_cndmask_b32_e64 v18, v19, v18, s[36:37]
	v_lshlrev_b32_e32 v64, 7, v18
	v_add_u32_e32 v18, v18, v7
	v_mul_lo_u32 v65, v18, s18
	v_or_b32_e32 v18, 7, v16
	v_or_b32_e32 v19, 8, v11
	v_cndmask_b32_e64 v18, v19, v18, s[36:37]
	v_lshlrev_b32_e32 v66, 7, v18
	v_add_u32_e32 v18, v18, v7
	v_mul_lo_u32 v67, v18, s18
	v_or_b32_e32 v18, 6, v16
	v_or_b32_e32 v19, 9, v11
	v_cndmask_b32_e64 v18, v19, v18, s[36:37]
	v_lshlrev_b32_e32 v68, 7, v18
	v_add_u32_e32 v18, v18, v7
	v_mul_lo_u32 v69, v18, s18
	v_or_b32_e32 v18, 5, v16
	v_or_b32_e32 v19, 10, v11
	v_cndmask_b32_e64 v18, v19, v18, s[36:37]
	v_lshlrev_b32_e32 v70, 7, v18
	v_add_u32_e32 v18, v18, v7
	v_mul_lo_u32 v71, v18, s18
	v_or_b32_e32 v18, 4, v16
	v_or_b32_e32 v19, 11, v11
	v_cndmask_b32_e64 v18, v19, v18, s[36:37]
	v_lshlrev_b32_e32 v72, 7, v18
	v_add_u32_e32 v18, v18, v7
	v_mul_lo_u32 v73, v18, s18
	v_or_b32_e32 v18, 3, v16
	v_or_b32_e32 v19, 12, v11
	v_cndmask_b32_e64 v18, v19, v18, s[36:37]
	v_lshlrev_b32_e32 v74, 7, v18
	v_add_u32_e32 v18, v18, v7
	v_or_b32_e32 v17, 15, v16
	v_mul_lo_u32 v75, v18, s18
	v_or_b32_e32 v18, 2, v16
	v_or_b32_e32 v19, 13, v11
	v_cndmask_b32_e64 v17, v11, v17, s[36:37]
	v_cndmask_b32_e64 v18, v19, v18, s[36:37]
	v_or_b32_e32 v19, 14, v11
	v_or_b32_e32 v11, 15, v11
	v_cndmask_b32_e64 v11, v11, v16, s[36:37]
	v_readlane_b32 s7, v253, 52
	v_lshlrev_b32_e32 v80, 7, v11
	v_add_u32_e32 v11, v11, v7
	v_lshlrev_b32_e32 v45, 10, v12
	v_mul_lo_u32 v81, v11, s18
	v_lshlrev_b32_e32 v11, 8, v13
	v_add_u32_e32 v12, s7, v45
	v_and_b32_e32 v9, 7, v154
	v_add3_u32 v46, v12, v11, v0
	v_and_b32_e32 v11, 0x3fffff3f, v154
	v_lshlrev_b32_e32 v76, 7, v18
	v_add_u32_e32 v18, v18, v7
	v_lshl_add_u32 v47, v11, 2, s7
	v_lshlrev_b32_e32 v11, 5, v9
	v_bfe_u32 v5, v5, 1, 5
	v_mul_lo_u32 v77, v18, s18
	v_or_b32_e32 v18, 1, v16
	v_add_u32_e32 v12, 0, v11
	v_add_u32_e32 v48, s7, v11
	v_and_b32_e32 v11, 4, v5
	v_bfe_u32 v41, v154, 3, 6
	v_cndmask_b32_e64 v18, v19, v18, s[36:37]
	v_bitop3_b32 v11, v11, v9, v38 bitop3:0x36
	v_xor_b32_e32 v5, v5, v154
	v_add_u32_e32 v40, s7, v0
	v_lshlrev_b32_e32 v31, 7, v17
	v_add_u32_e32 v17, v17, v7
	v_lshlrev_b32_e32 v78, 7, v18
	v_add_u32_e32 v18, v18, v7
	v_cmp_eq_u32_e64 s[38:39], 0, v13
	v_cmp_lt_u32_e64 s[42:43], 1, v13
	v_cmp_eq_u32_e64 s[44:45], 3, v13
	v_cmp_gt_u32_e64 s[46:47], 2, v13
	v_or_b32_e32 v7, v16, v7
	v_lshlrev_b32_e32 v13, 7, v41
	v_lshl_add_u32 v16, v11, 4, 0
	v_lshlrev_b32_e32 v5, 4, v5
	s_movk_i32 s7, 0x70
	v_lshrrev_b32_e32 v11, 5, v154
	v_mul_lo_u32 v79, v18, s18
	v_and_or_b32 v18, v5, s7, v13
	v_bfe_u32 v5, v41, 1, 1
	v_and_b32_e32 v11, 6, v11
	v_bitop3_b32 v5, v5, v9, v11 bitop3:0x36
	v_lshrrev_b32_e32 v8, 2, v140
	v_bfe_u32 v10, v154, 4, 2
	v_lshl_or_b32 v20, v5, 4, v13
	v_lshlrev_b32_e32 v5, 10, v3
	v_lshlrev_b32_e32 v49, 1, v3
	v_lshrrev_b32_e32 v3, 1, v39
	v_or_b32_e32 v22, v38, v37
	s_movk_i32 s7, 0x80
	v_lshl_or_b32 v8, v10, 3, v8
	v_bitop3_b32 v24, v22, v3, 1 bitop3:0x36
	v_lshlrev_b32_e32 v4, 3, v9
	v_cmp_gt_i32_e64 s[48:49], s7, v154
	v_readlane_b32 s7, v253, 48
	v_or_b32_e32 v9, 32, v8
	v_lshlrev_b32_e32 v11, 8, v8
	v_or_b32_e32 v23, v22, v3
	v_lshlrev_b32_e32 v24, 4, v24
	v_lshl_add_u32 v23, v23, 4, s7
	v_add3_u32 v91, s7, v24, v11
	v_lshlrev_b32_e32 v24, 8, v9
	v_add_u32_e32 v90, v23, v11
	v_add_u32_e32 v92, v23, v24
	v_or_b32_e32 v23, 2, v3
	v_bitop3_b32 v25, v38, v23, v37 bitop3:0x36
	v_bitop3_b32 v23, v22, v23, 1 bitop3:0x36
	v_lshlrev_b32_e32 v23, 4, v23
	v_lshl_add_u32 v25, v25, 4, s7
	v_add3_u32 v94, s7, v23, v11
	v_or_b32_e32 v23, 4, v3
	v_add_u32_e32 v93, v25, v11
	v_add_u32_e32 v95, v25, v24
	v_bitop3_b32 v25, v38, v23, v37 bitop3:0x36
	v_bitop3_b32 v23, v22, v23, 1 bitop3:0x36
	v_lshlrev_b32_e32 v23, 4, v23
	v_lshl_add_u32 v25, v25, 4, s7
	v_add3_u32 v97, s7, v23, v11
	v_or_b32_e32 v23, 6, v3
	v_add_u32_e32 v96, v25, v11
	v_add_u32_e32 v98, v25, v24
	v_bitop3_b32 v25, v38, v23, v37 bitop3:0x36
	v_bitop3_b32 v23, v22, v23, 1 bitop3:0x36
	v_lshlrev_b32_e32 v23, 4, v23
	v_lshl_add_u32 v25, v25, 4, s7
	v_add3_u32 v100, s7, v23, v11
	v_or_b32_e32 v23, 8, v3
	v_add_u32_e32 v99, v25, v11
	v_add_u32_e32 v101, v25, v24
	v_bitop3_b32 v25, v38, v23, v37 bitop3:0x36
	v_bitop3_b32 v23, v22, v23, 1 bitop3:0x36
	v_lshlrev_b32_e32 v23, 4, v23
	v_lshl_add_u32 v25, v25, 4, s7
	v_add3_u32 v103, s7, v23, v11
	v_or_b32_e32 v23, 10, v3
	v_add_u32_e32 v102, v25, v11
	v_add_u32_e32 v104, v25, v24
	v_bitop3_b32 v25, v38, v23, v37 bitop3:0x36
	v_bitop3_b32 v23, v22, v23, 1 bitop3:0x36
	v_lshlrev_b32_e32 v23, 4, v23
	v_lshl_add_u32 v25, v25, 4, s7
	v_add3_u32 v106, s7, v23, v11
	v_or_b32_e32 v23, 12, v3
	v_add_u32_e32 v105, v25, v11
	v_add_u32_e32 v107, v25, v24
	v_bitop3_b32 v25, v38, v23, v37 bitop3:0x36
	v_bitop3_b32 v23, v22, v23, 1 bitop3:0x36
	v_lshlrev_b32_e32 v23, 4, v23
	v_or_b32_e32 v3, 14, v3
	v_add3_u32 v109, s7, v23, v11
	v_bitop3_b32 v23, v38, v3, v37 bitop3:0x36
	v_bitop3_b32 v3, v22, v3, 1 bitop3:0x36
	s_or_b64 s[2:3], s[36:37], s[38:39]
	v_lshl_add_u32 v25, v25, 4, s7
	v_lshl_add_u32 v23, v23, 4, s7
	v_lshlrev_b32_e32 v3, 4, v3
	v_lshlrev_b32_e32 v27, 7, v8
	v_lshlrev_b32_e32 v8, 3, v39
	v_mul_lo_u32 v17, v17, s18
	v_mul_lo_u32 v7, v7, s18
	v_add_u32_e32 v108, v25, v11
	v_add_u32_e32 v111, v23, v11
	v_add3_u32 v3, s7, v3, v11
	s_and_b64 s[18:19], s[26:27], exec
	v_and_b32_e32 v11, 16, v8
	v_lshrrev_b32_e32 v8, 3, v140
	v_add_u32_e32 v110, v25, v24
	v_add_u32_e32 v113, v23, v24
	v_lshlrev_b32_e32 v26, 7, v9
	v_or_b32_e32 v24, v38, v8
	v_lshl_add_u64 v[8:9], s[24:25], 0, v[0:1]
	s_mov_b64 s[18:19], 0x2e088000
	v_lshl_add_u64 v[22:23], v[8:9], 0, s[18:19]
	v_bitop3_b32 v8, s6, v24, 3 bitop3:0x6c
	s_cselect_b32 s20, 0, 0x4000
	s_and_b32 s18, s6, 3
	v_lshl_or_b32 v28, v8, 5, v11
	v_lshlrev_b32_e32 v8, 11, v10
	v_add_u32_e32 v83, s7, v145
	v_add_u32_e32 v86, s7, v147
	s_ashr_i32 s7, s6, 2
	v_lshl_or_b32 v8, s18, 13, v8
	v_mov_b32_e32 v9, v1
	s_lshl_b32 s19, s7, 13
	v_lshl_add_u64 v[8:9], s[24:25], 0, v[8:9]
	v_lshlrev_b32_e32 v10, 2, v140
	v_mov_b32_e32 v11, v1
	v_readlane_b32 s68, v254, 4
	s_add_i32 s26, s19, 0
	v_lshl_add_u64 v[8:9], v[8:9], 0, v[10:11]
	s_mov_b64 s[18:19], 0x25e88000
	v_readlane_b32 s71, v254, 7
	v_readlane_b32 s75, v254, 11
	v_lshl_add_u64 v[24:25], v[8:9], 0, s[18:19]
	v_readlane_b32 s70, v254, 6
	v_readlane_b32 s74, v254, 10
	v_mov_b32_e32 v8, s71
	v_mov_b32_e32 v9, s75
	v_add3_u32 v11, s26, v26, v28
	v_cndmask_b32_e64 v9, v8, v9, s[36:37]
	v_mov_b32_e32 v8, s70
	v_mov_b32_e32 v26, s74
	v_cndmask_b32_e64 v8, v8, v26, s[36:37]
	v_readlane_b32 s60, v254, 0
	v_readlane_b32 s73, v254, 9
	v_lshl_add_u64 v[8:9], v[8:9], 0, s[20:21]
	v_readlane_b32 s61, v254, 1
	v_add_u32_e32 v15, 0, v0
	v_add3_u32 v10, s26, v27, v28
	v_readlane_b32 s72, v254, 8
	v_lshl_add_u64 v[26:27], v[8:9], 0, v[0:1]
	v_mov_b32_e32 v0, s73
	v_mov_b32_e32 v8, s61
	v_and_b32_e32 v2, 0x78, v2
	s_movk_i32 s0, 0x100
	v_mul_u32_u24_e32 v84, 0x110, v41
	v_cndmask_b32_e64 v29, v0, v8, s[36:37]
	v_mov_b32_e32 v0, s72
	v_mov_b32_e32 v8, s60
	v_cmp_gt_u32_e64 s[0:1], s0, v154
	v_mov_b32_e32 v19, v1
	v_mov_b32_e32 v21, v1
	s_lshl_b32 s6, s7, 1
	v_cndmask_b32_e64 v28, v0, v8, s[36:37]
	v_lshlrev_b32_e32 v0, 1, v2
	v_lshlrev_b32_e32 v30, 1, v4
	v_lshlrev_b32_e32 v32, 1, v6
	v_add_u32_e32 v50, v14, v31
	v_add_u32_e32 v51, v15, v17
	v_add_u32_e32 v52, v14, v33
	v_add_u32_e32 v53, v15, v34
	v_add_u32_e32 v54, v14, v35
	v_add_u32_e32 v55, v15, v55
	v_add_u32_e32 v56, v14, v56
	v_add_u32_e32 v57, v15, v57
	v_add_u32_e32 v58, v14, v58
	v_add_u32_e32 v59, v15, v59
	v_add_u32_e32 v60, v14, v60
	v_add_u32_e32 v61, v15, v61
	v_add_u32_e32 v62, v14, v62
	v_add_u32_e32 v63, v15, v63
	v_add_u32_e32 v64, v14, v64
	v_add_u32_e32 v65, v15, v65
	v_add_u32_e32 v66, v14, v66
	v_add_u32_e32 v67, v15, v67
	v_add_u32_e32 v68, v14, v68
	v_add_u32_e32 v69, v15, v69
	v_add_u32_e32 v70, v14, v70
	v_add_u32_e32 v71, v15, v71
	v_add_u32_e32 v72, v14, v72
	v_add_u32_e32 v73, v15, v73
	v_add_u32_e32 v74, v14, v74
	v_add_u32_e32 v75, v15, v75
	v_add_u32_e32 v76, v14, v76
	v_add_u32_e32 v77, v15, v77
	v_add_u32_e32 v78, v14, v78
	v_add_u32_e32 v79, v15, v79
	v_add_u32_e32 v80, v14, v80
	v_add_u32_e32 v81, v15, v81
	v_add_u32_e32 v82, v15, v7
	v_add_u32_e32 v83, v83, v144
	v_add_u32_e32 v84, v12, v84
	v_add_u32_e32 v85, v16, v13
	v_add_u32_e32 v86, v86, v146
	v_add_u32_e32 v87, v40, v5
	v_add_u32_e32 v88, v10, v36
	v_add_u32_e32 v89, v11, v36
	v_add_u32_e32 v90, v90, v36
	v_add_u32_e32 v91, v91, v36
	v_add_u32_e32 v92, v92, v36
	v_add_u32_e32 v93, v93, v36
	v_add_u32_e32 v94, v94, v36
	v_add_u32_e32 v95, v95, v36
	v_add_u32_e32 v96, v96, v36
	v_add_u32_e32 v97, v97, v36
	v_add_u32_e32 v98, v98, v36
	v_add_u32_e32 v99, v99, v36
	v_add_u32_e32 v100, v100, v36
	v_add_u32_e32 v101, v101, v36
	v_add_u32_e32 v102, v102, v36
	v_add_u32_e32 v103, v103, v36
	v_add_u32_e32 v104, v104, v36
	v_add_u32_e32 v105, v105, v36
	v_add_u32_e32 v106, v106, v36
	v_add_u32_e32 v107, v107, v36
	v_add_u32_e32 v108, v108, v36
	v_add_u32_e32 v109, v109, v36
	v_add_u32_e32 v110, v110, v36
	v_add_u32_e32 v111, v111, v36
	v_add_u32_e32 v112, v3, v36
	v_add_u32_e32 v113, v113, v36
	s_mov_b32 s18, s84
	v_readlane_b32 s69, v254, 5
	v_readlane_b32 s62, v254, 2
	v_readlane_b32 s63, v254, 3
	s_mov_b32 s26, s18
	s_cmpk_lt_i32 s26, 0x820
	s_cbranch_scc0 .Lpf_h_skip
	s_ashr_i32 s19, s26, 2
	s_mul_hi_i32 s7, s19, 0x7e07e07f
	s_lshr_b32 s20, s7, 31
	s_ashr_i32 s7, s7, 7
	s_add_i32 s7, s7, s20
	s_mul_i32 s29, s7, 0xfffffefc
	s_add_i32 s29, s29, s19
	s_and_b32 s30, s26, 3
	s_cmp_gt_i32 s29, 3
	s_cbranch_scc0 .Lpf_h_ctx
	s_lshl_b32 s19, s7, 14
	s_lshl_b32 s20, s29, 6
	s_add_i32 s19, s19, s20
	s_addk_i32 s19, 0xff00
	s_branch .Lpf_h_tb
.Lpf_h_ctx:
	s_lshl_b32 s19, s7, 8
	s_lshl_b32 s20, s29, 6
	s_add_i32 s19, s19, s20
	s_add_i32 s19, s19, 0x8000
.Lpf_h_tb:
	s_lshl_b32 s26, s30, 8
	s_mov_b32 s27, s21
	s_lshl_b32 s20, s30, 7
	v_mov_b64_e32 v[178:179], s[16:17]
	v_add_u32_e32 v176, s19, v142
	v_mad_i64_i32 v[176:177], vcc, v176, s79, v[178:179]
	v_lshl_add_u64 v[176:177], v[176:177], 0, s[26:27]
	v_lshl_add_u64 v[176:177], v[176:177], 0, v[0:1]
	v_add_co_u32_e32 v176, vcc, 0x1000, v176
	s_nop 1
	v_addc_co_u32_e32 v177, vcc, 0, v177, vcc
	global_load_dwordx4 v[156:159], v[176:177], off
	v_add_u32_e32 v176, s19, v143
	v_mad_i64_i32 v[176:177], vcc, v176, s79, v[178:179]
	v_lshl_add_u64 v[176:177], v[176:177], 0, s[26:27]
	v_lshl_add_u64 v[176:177], v[176:177], 0, v[0:1]
	v_add_co_u32_e32 v176, vcc, 0x1000, v176
	s_nop 1
	v_addc_co_u32_e32 v177, vcc, 0, v177, vcc
	global_load_dwordx4 v[160:163], v[176:177], off
	v_add_u32_e32 v176, s19, v41
	v_mad_i64_i32 v[176:177], vcc, v176, s79, v[178:179]
	v_lshl_add_u64 v[176:177], v[176:177], 0, s[20:21]
	v_mov_b32_e32 v180, v30
	v_mov_b32_e32 v181, 0
	v_lshl_add_u64 v[176:177], v[176:177], 0, v[180:181]
	global_load_dwordx4 v[164:167], v[176:177], off offset:3584
	global_load_dwordx4 v[168:171], v[176:177], off offset:3072
	v_add_u32_e32 v176, s19, v42
	v_mov_b64_e32 v[178:179], s[24:25]
	v_mad_i64_i32 v[176:177], vcc, v176, s79, v[178:179]
	v_mov_b32_e32 v180, v32
	v_lshl_add_u64 v[176:177], v[176:177], 0, v[180:181]
	v_add_co_u32_e32 v176, vcc, 0x13802000, v176
	s_nop 1
	v_addc_co_u32_e32 v177, vcc, 0, v177, vcc
	global_load_dwordx2 v[172:173], v[176:177], off offset:1024

.LBB0_217:
	s_or_b64 exec, exec, s[26:27]
	s_waitcnt lgkmcnt(0)
	s_barrier
	ds_read_b64_tr_b16 v[6:7], v88 offset:34816
	ds_read_b64_tr_b16 v[8:9], v88 offset:35328
	ds_read_b64_tr_b16 v[2:3], v89 offset:34816
	ds_read_b64_tr_b16 v[4:5], v89 offset:35328
	ds_read_b64_tr_b16 v[12:13], v90
	ds_read_b64_tr_b16 v[14:15], v91 offset:1024
	ds_read_b64_tr_b16 v[114:115], v92
	ds_read_b64_tr_b16 v[116:117], v91 offset:9216
	s_add_i32 s7, s7, s6
	s_waitcnt lgkmcnt(2)
	v_mfma_f32_16x16x32_bf16 v[12:15], v[6:9], v[12:15], 0
	s_mulk_i32 s7, 0x104
	s_add_i32 s7, s7, s29
	s_lshl_b32 s7, s7, 2
	s_or_b32 s26, s7, s30
	s_waitcnt lgkmcnt(0)
	v_mfma_f32_16x16x32_bf16 v[12:15], v[2:5], v[114:117], v[12:15]
	s_ashr_i32 s27, s26, 31
	s_lshl_b64 s[26:27], s[26:27], 15
	v_lshl_add_u64 v[10:11], v[24:25], 0, s[26:27]
	s_add_i32 s26, s18, s28
	s_cmpk_lt_i32 s26, 0x820
	s_cbranch_scc0 .Lpf_t_skip
	s_ashr_i32 s19, s26, 2
	s_mul_hi_i32 s7, s19, 0x7e07e07f
	s_lshr_b32 s20, s7, 31
	s_ashr_i32 s7, s7, 7
	s_add_i32 s7, s7, s20
	s_mul_i32 s29, s7, 0xfffffefc
	s_add_i32 s29, s29, s19
	s_and_b32 s30, s26, 3
	s_cmp_gt_i32 s29, 3
	s_cbranch_scc0 .Lpf_t_ctx
	s_lshl_b32 s19, s7, 14
	s_lshl_b32 s20, s29, 6
	s_add_i32 s19, s19, s20
	s_addk_i32 s19, 0xff00
	s_branch .Lpf_t_tb

.Lpf_t_skip:
	s_nop 4
	global_store_dword v[10:11], v12, off
	global_store_dword v[10:11], v13, off offset:512
	global_store_dword v[10:11], v14, off offset:1024
	global_store_dword v[10:11], v15, off offset:1536
	ds_read_b64_tr_b16 v[12:13], v93
	ds_read_b64_tr_b16 v[14:15], v94 offset:1024
	ds_read_b64_tr_b16 v[114:115], v95
	ds_read_b64_tr_b16 v[116:117], v94 offset:9216
	s_waitcnt lgkmcnt(2)
	v_mfma_f32_16x16x32_bf16 v[12:15], v[6:9], v[12:15], 0
	s_waitcnt lgkmcnt(0)
	v_mfma_f32_16x16x32_bf16 v[12:15], v[2:5], v[114:117], v[12:15]
	s_nop 7
	global_store_dword v[10:11], v12, off offset:64
	global_store_dword v[10:11], v13, off offset:576
	global_store_dword v[10:11], v14, off offset:1088
	global_store_dword v[10:11], v15, off offset:1600
	ds_read_b64_tr_b16 v[12:13], v96
	ds_read_b64_tr_b16 v[14:15], v97 offset:1024
	ds_read_b64_tr_b16 v[114:115], v98
	ds_read_b64_tr_b16 v[116:117], v97 offset:9216
	s_waitcnt lgkmcnt(2)
	v_mfma_f32_16x16x32_bf16 v[12:15], v[6:9], v[12:15], 0
	s_waitcnt lgkmcnt(0)
	v_mfma_f32_16x16x32_bf16 v[12:15], v[2:5], v[114:117], v[12:15]
	s_nop 7
	global_store_dword v[10:11], v12, off offset:128
	global_store_dword v[10:11], v13, off offset:640
	global_store_dword v[10:11], v14, off offset:1152
	global_store_dword v[10:11], v15, off offset:1664
	ds_read_b64_tr_b16 v[12:13], v99
	ds_read_b64_tr_b16 v[14:15], v100 offset:1024
	ds_read_b64_tr_b16 v[114:115], v101
	ds_read_b64_tr_b16 v[116:117], v100 offset:9216
	s_waitcnt lgkmcnt(2)
	v_mfma_f32_16x16x32_bf16 v[12:15], v[6:9], v[12:15], 0
	s_waitcnt lgkmcnt(0)
	v_mfma_f32_16x16x32_bf16 v[12:15], v[2:5], v[114:117], v[12:15]
	s_nop 7
	global_store_dword v[10:11], v12, off offset:192
	global_store_dword v[10:11], v13, off offset:704
	global_store_dword v[10:11], v14, off offset:1216
	global_store_dword v[10:11], v15, off offset:1728
	ds_read_b64_tr_b16 v[12:13], v102
	ds_read_b64_tr_b16 v[14:15], v103 offset:1024
	ds_read_b64_tr_b16 v[114:115], v104
	ds_read_b64_tr_b16 v[116:117], v103 offset:9216
	s_waitcnt lgkmcnt(2)
	v_mfma_f32_16x16x32_bf16 v[12:15], v[6:9], v[12:15], 0
	s_waitcnt lgkmcnt(0)
	v_mfma_f32_16x16x32_bf16 v[12:15], v[2:5], v[114:117], v[12:15]
	s_nop 7
	global_store_dword v[10:11], v12, off offset:256
	global_store_dword v[10:11], v13, off offset:768
	global_store_dword v[10:11], v14, off offset:1280
	global_store_dword v[10:11], v15, off offset:1792
	ds_read_b64_tr_b16 v[12:13], v105
	ds_read_b64_tr_b16 v[14:15], v106 offset:1024
	ds_read_b64_tr_b16 v[114:115], v107
	ds_read_b64_tr_b16 v[116:117], v106 offset:9216
	s_waitcnt lgkmcnt(2)
	v_mfma_f32_16x16x32_bf16 v[12:15], v[6:9], v[12:15], 0
	s_waitcnt lgkmcnt(0)
	v_mfma_f32_16x16x32_bf16 v[12:15], v[2:5], v[114:117], v[12:15]
	s_nop 7
	global_store_dword v[10:11], v12, off offset:320
	global_store_dword v[10:11], v13, off offset:832
	global_store_dword v[10:11], v14, off offset:1344
	global_store_dword v[10:11], v15, off offset:1856
	ds_read_b64_tr_b16 v[12:13], v108
	ds_read_b64_tr_b16 v[14:15], v109 offset:1024
	ds_read_b64_tr_b16 v[114:115], v110
	ds_read_b64_tr_b16 v[116:117], v109 offset:9216
	s_waitcnt lgkmcnt(2)
	v_mfma_f32_16x16x32_bf16 v[12:15], v[6:9], v[12:15], 0
	s_waitcnt lgkmcnt(0)
	v_mfma_f32_16x16x32_bf16 v[12:15], v[2:5], v[114:117], v[12:15]
	s_nop 7
	global_store_dword v[10:11], v12, off offset:384
	global_store_dword v[10:11], v13, off offset:896
	global_store_dword v[10:11], v14, off offset:1408
	global_store_dword v[10:11], v15, off offset:1920
	ds_read_b64_tr_b16 v[12:13], v111
	ds_read_b64_tr_b16 v[14:15], v112 offset:1024
	s_waitcnt lgkmcnt(0)
	v_mfma_f32_16x16x32_bf16 v[6:9], v[6:9], v[12:15], 0
	ds_read_b64_tr_b16 v[12:13], v113
	ds_read_b64_tr_b16 v[14:15], v112 offset:9216
	s_waitcnt lgkmcnt(0)
	v_mfma_f32_16x16x32_bf16 v[2:5], v[2:5], v[12:15], v[6:9]
	s_nop 7
	global_store_dword v[10:11], v2, off offset:448
	global_store_dword v[10:11], v3, off offset:960
	global_store_dword v[10:11], v4, off offset:1472
	global_store_dword v[10:11], v5, off offset:1984
	s_barrier
	s_load_dword s7, s[98:99], 0x10
	s_waitcnt lgkmcnt(0)
	s_lshr_b32 s7, s7, 16
	s_cmp_lg_u32 s7, 0
	s_cselect_b64 s[26:27], -1, 0
	s_cmp_lg_u64 s[26:27], 0
	s_addc_u32 s18, s18, s28
	s_cmpk_lt_i32 s18, 0x820
	s_cbranch_scc0 .LBB0_254

.LBB0_222:
	v_add_u32_e32 v2, s19, v142
	v_mov_b64_e32 v[10:11], s[16:17]
	s_and_b32 s30, s18, 3
	v_mad_i64_i32 v[2:3], s[26:27], v2, s79, v[10:11]
	s_lshl_b32 s26, s30, 8
	s_mov_b32 s27, s21
	v_lshl_add_u64 v[2:3], v[2:3], 0, s[26:27]
	v_lshl_add_u64 v[2:3], v[2:3], 0, v[0:1]
	v_add_co_u32_e32 v2, vcc, 0x1000, v2
	v_add_u32_e32 v12, s19, v41
	s_nop 0
	v_addc_co_u32_e32 v3, vcc, 0, v3, vcc
	s_waitcnt vmcnt(0)
	v_mov_b32_e32 v6, v156
	v_mov_b32_e32 v7, v157
	v_mov_b32_e32 v8, v158
	v_mov_b32_e32 v9, v159
	v_add_u32_e32 v2, s19, v143
	s_lshl_b32 s20, s30, 7
	v_mad_i64_i32 v[2:3], s[40:41], v2, s79, v[10:11]
	v_mad_i64_i32 v[10:11], s[40:41], v12, s79, v[10:11]
	v_lshl_add_u64 v[2:3], v[2:3], 0, s[26:27]
	v_lshl_add_u64 v[10:11], v[10:11], 0, s[20:21]
	v_mov_b32_e32 v31, v1
	v_lshl_add_u64 v[2:3], v[2:3], 0, v[0:1]
	v_lshl_add_u64 v[10:11], v[10:11], 0, v[30:31]
	v_add_u32_e32 v31, s19, v42
	v_mov_b64_e32 v[34:35], s[24:25]
	v_add_co_u32_e32 v2, vcc, 0x1000, v2
	v_mad_i64_i32 v[34:35], s[40:41], v31, s79, v[34:35]
	v_mov_b32_e32 v33, v1
	v_addc_co_u32_e32 v3, vcc, 0, v3, vcc
	v_lshl_add_u64 v[34:35], v[34:35], 0, v[32:33]
	s_mov_b32 s19, 0x13802000
	v_add_co_u32_e32 v34, vcc, s19, v34
	v_mov_b32_e32 v2, v160
	v_mov_b32_e32 v3, v161
	v_mov_b32_e32 v4, v162
	v_mov_b32_e32 v5, v163
	s_nop 0
	v_addc_co_u32_e32 v35, vcc, 0, v35, vcc
	v_mov_b32_e32 v14, v164
	v_mov_b32_e32 v15, v165
	v_mov_b32_e32 v16, v166
	v_mov_b32_e32 v17, v167
	s_nop 0
	v_mov_b32_e32 v10, v168
	v_mov_b32_e32 v11, v169
	v_mov_b32_e32 v12, v170
	v_mov_b32_e32 v13, v171
	v_lshl_add_u64 v[126:127], v[26:27], 0, s[26:27]
	v_mov_b32_e32 v34, v172
	v_mov_b32_e32 v35, v173
	s_movk_i32 s19, 0x2000
	s_waitcnt vmcnt(0)
	v_lshlrev_b32_e32 v114, 16, v34
	v_and_b32_e32 v115, 0xffff0000, v34
	v_lshlrev_b32_e32 v116, 16, v35
	v_and_b32_e32 v117, 0xffff0000, v35
	ds_write_b128 v43, v[114:117]
	v_add_co_u32_e32 v116, vcc, s52, v126
	global_load_dword v33, v[126:127], off
	global_load_dword v35, v[126:127], off offset:1024
	global_load_dword v34, v[126:127], off offset:2048
	global_load_dword v31, v[126:127], off offset:3072
	v_addc_co_u32_e32 v117, vcc, 0, v127, vcc
	v_add_co_u32_e32 v128, vcc, s19, v126
	s_movk_i32 s19, 0x3000
	s_nop 0
	v_addc_co_u32_e32 v129, vcc, 0, v127, vcc
	v_add_co_u32_e32 v126, vcc, s19, v126
	global_load_dword v114, v[128:129], off offset:-4096
	global_load_dword v125, v[116:117], off offset:1024
	global_load_dword v124, v[116:117], off offset:2048
	global_load_dword v122, v[116:117], off offset:3072
	global_load_dword v119, v[128:129], off
	global_load_dword v123, v[128:129], off offset:1024
	global_load_dword v120, v[128:129], off offset:2048
	s_nop 0
	global_load_dword v116, v[128:129], off offset:3072
	v_addc_co_u32_e32 v127, vcc, 0, v127, vcc
	global_load_dword v117, v[126:127], off
	global_load_dword v121, v[126:127], off offset:1024
	global_load_dword v118, v[126:127], off offset:2048
	global_load_dword v115, v[126:127], off offset:3072
	v_lshl_or_b32 v126, v44, 2, s26
	v_mov_b32_e32 v127, v1
	v_lshl_add_u64 v[126:127], v[28:29], 0, v[126:127]
	global_load_dword v126, v[126:127], off
	s_waitcnt lgkmcnt(0)
	s_barrier
	ds_read_b128 v[128:131], v50
	ds_read_b128 v[132:135], v50 offset:16
	ds_read_b128 v[136:139], v50 offset:32
	ds_read_b128 v[148:151], v50 offset:48
	s_mov_b32 s19, 0xbd800000
	s_mov_b64 s[26:27], 0
	s_waitcnt vmcnt(15) lgkmcnt(3)
	v_mul_f32_e32 v127, v35, v129
	v_fmac_f32_e32 v127, v33, v128
	s_waitcnt vmcnt(14)
	v_fmac_f32_e32 v127, v34, v130
	s_waitcnt vmcnt(13)
	v_fmac_f32_e32 v127, v31, v131
	s_waitcnt vmcnt(11) lgkmcnt(2)
	v_mul_f32_e32 v128, v125, v133
	v_fmac_f32_e32 v128, v114, v132
	s_waitcnt vmcnt(10)
	v_fmac_f32_e32 v128, v124, v134
	s_waitcnt vmcnt(9)
	v_fmac_f32_e32 v128, v122, v135
	s_waitcnt vmcnt(0)
	v_add_f32_e32 v127, v126, v127
	v_add_f32_e32 v127, v127, v128
	s_waitcnt lgkmcnt(1)
	v_mul_f32_e32 v128, v123, v137
	v_fmac_f32_e32 v128, v119, v136
	v_fmac_f32_e32 v128, v120, v138
	v_fmac_f32_e32 v128, v116, v139
	v_add_f32_e32 v127, v127, v128
	s_waitcnt lgkmcnt(0)
	v_mul_f32_e32 v128, v121, v149
	v_fmac_f32_e32 v128, v117, v148
	v_fmac_f32_e32 v128, v118, v150
	v_fmac_f32_e32 v128, v115, v151
	v_add_f32_e32 v127, v127, v128
	v_max_f32_e64 v128, -v127, 0
	v_mul_f32_e64 v127, |v127|, s80
	v_exp_f32_e32 v127, v127
	s_nop 0
	v_add_f32_e32 v127, 1.0, v127
	v_cmp_gt_f32_e32 vcc, s33, v127
	s_nop 1
	v_cndmask_b32_e64 v129, 0, 32, vcc
	v_ldexp_f32 v127, v127, v129
	v_log_f32_e32 v127, v127
	s_nop 0
	v_mul_f32_e32 v129, 0x3f317217, v127
	v_fma_f32 v129, v127, s81, -v129
	v_fmac_f32_e32 v129, 0x3377d1cf, v127
	v_fmac_f32_e32 v129, 0x3f317217, v127
	v_cmp_lt_f32_e64 s[50:51], |v127|, s82
	s_nop 1
	v_cndmask_b32_e64 v127, v127, v129, s[50:51]
	v_cndmask_b32_e32 v129, 0, v217, vcc
	v_sub_f32_e32 v127, v127, v129
	v_add_f32_e32 v127, v128, v127
	v_fma_f32 v127, v127, s19, 0
	ds_write_b32 v51, v127
	ds_read_b128 v[128:131], v52
	ds_read_b128 v[132:135], v52 offset:16
	ds_read_b128 v[136:139], v52 offset:32
	ds_read_b128 v[148:151], v52 offset:48
	s_waitcnt lgkmcnt(3)
	v_mul_f32_e32 v129, v35, v129
	v_fmac_f32_e32 v129, v33, v128
	v_fmac_f32_e32 v129, v34, v130
	v_fmac_f32_e32 v129, v31, v131
	v_add_f32_e32 v128, v126, v129
	s_waitcnt lgkmcnt(2)
	v_mul_f32_e32 v129, v125, v133
	v_fmac_f32_e32 v129, v114, v132
	v_fmac_f32_e32 v129, v124, v134
	v_fmac_f32_e32 v129, v122, v135
	v_add_f32_e32 v128, v128, v129
	s_waitcnt lgkmcnt(1)
	v_mul_f32_e32 v129, v123, v137
	v_fmac_f32_e32 v129, v119, v136
	v_fmac_f32_e32 v129, v120, v138
	v_fmac_f32_e32 v129, v116, v139
	v_add_f32_e32 v128, v128, v129
	s_waitcnt lgkmcnt(0)
	v_mul_f32_e32 v129, v121, v149
	v_fmac_f32_e32 v129, v117, v148
	v_fmac_f32_e32 v129, v118, v150
	v_fmac_f32_e32 v129, v115, v151
	v_add_f32_e32 v128, v128, v129
	v_max_f32_e64 v129, -v128, 0
	v_mul_f32_e64 v128, |v128|, s80
	v_exp_f32_e32 v128, v128
	s_nop 0
	v_add_f32_e32 v128, 1.0, v128
	v_cmp_gt_f32_e32 vcc, s33, v128
	s_nop 1
	v_cndmask_b32_e64 v130, 0, 32, vcc
	v_ldexp_f32 v128, v128, v130
	v_log_f32_e32 v128, v128
	s_nop 0
	v_mul_f32_e32 v130, 0x3f317217, v128
	v_fma_f32 v130, v128, s81, -v130
	v_fmac_f32_e32 v130, 0x3377d1cf, v128
	v_fmac_f32_e32 v130, 0x3f317217, v128
	v_cmp_lt_f32_e64 s[50:51], |v128|, s82
	s_nop 1
	v_cndmask_b32_e64 v128, v128, v130, s[50:51]
	v_cndmask_b32_e32 v130, 0, v217, vcc
	v_sub_f32_e32 v128, v128, v130
	v_add_f32_e32 v128, v129, v128
	v_fmac_f32_e32 v127, 0xbd800000, v128
	ds_write_b32 v53, v127
	ds_read_b128 v[128:131], v54
	ds_read_b128 v[132:135], v54 offset:16
	ds_read_b128 v[136:139], v54 offset:32
	ds_read_b128 v[148:151], v54 offset:48
	s_waitcnt lgkmcnt(3)
	v_mul_f32_e32 v129, v35, v129
	v_fmac_f32_e32 v129, v33, v128
	v_fmac_f32_e32 v129, v34, v130
	v_fmac_f32_e32 v129, v31, v131
	v_add_f32_e32 v128, v126, v129
	s_waitcnt lgkmcnt(2)
	v_mul_f32_e32 v129, v125, v133
	v_fmac_f32_e32 v129, v114, v132
	v_fmac_f32_e32 v129, v124, v134
	v_fmac_f32_e32 v129, v122, v135
	v_add_f32_e32 v128, v128, v129
	s_waitcnt lgkmcnt(1)
	v_mul_f32_e32 v129, v123, v137
	v_fmac_f32_e32 v129, v119, v136
	v_fmac_f32_e32 v129, v120, v138
	v_fmac_f32_e32 v129, v116, v139
	v_add_f32_e32 v128, v128, v129
	s_waitcnt lgkmcnt(0)
	v_mul_f32_e32 v129, v121, v149
	v_fmac_f32_e32 v129, v117, v148
	v_fmac_f32_e32 v129, v118, v150
	v_fmac_f32_e32 v129, v115, v151
	v_add_f32_e32 v128, v128, v129
	v_max_f32_e64 v129, -v128, 0
	v_mul_f32_e64 v128, |v128|, s80
	v_exp_f32_e32 v128, v128
	s_nop 0
	v_add_f32_e32 v128, 1.0, v128
	v_cmp_gt_f32_e32 vcc, s33, v128
	s_nop 1
	v_cndmask_b32_e64 v130, 0, 32, vcc
	v_ldexp_f32 v128, v128, v130
	v_log_f32_e32 v128, v128
	s_nop 0
	v_mul_f32_e32 v130, 0x3f317217, v128
	v_fma_f32 v130, v128, s81, -v130
	v_fmac_f32_e32 v130, 0x3377d1cf, v128
	v_fmac_f32_e32 v130, 0x3f317217, v128
	v_cmp_lt_f32_e64 s[50:51], |v128|, s82
	s_nop 1
	v_cndmask_b32_e64 v128, v128, v130, s[50:51]
	v_cndmask_b32_e32 v130, 0, v217, vcc
	v_sub_f32_e32 v128, v128, v130
	v_add_f32_e32 v128, v129, v128
	v_fmac_f32_e32 v127, 0xbd800000, v128
	ds_write_b32 v55, v127
	ds_read_b128 v[128:131], v56
	ds_read_b128 v[132:135], v56 offset:16
	ds_read_b128 v[136:139], v56 offset:32
	ds_read_b128 v[148:151], v56 offset:48
	s_waitcnt lgkmcnt(3)
	v_mul_f32_e32 v129, v35, v129
	v_fmac_f32_e32 v129, v33, v128
	v_fmac_f32_e32 v129, v34, v130
	v_fmac_f32_e32 v129, v31, v131
	v_add_f32_e32 v128, v126, v129
	s_waitcnt lgkmcnt(2)
	v_mul_f32_e32 v129, v125, v133
	v_fmac_f32_e32 v129, v114, v132
	v_fmac_f32_e32 v129, v124, v134
	v_fmac_f32_e32 v129, v122, v135
	v_add_f32_e32 v128, v128, v129
	s_waitcnt lgkmcnt(1)
	v_mul_f32_e32 v129, v123, v137
	v_fmac_f32_e32 v129, v119, v136
	v_fmac_f32_e32 v129, v120, v138
	v_fmac_f32_e32 v129, v116, v139
	v_add_f32_e32 v128, v128, v129
	s_waitcnt lgkmcnt(0)
	v_mul_f32_e32 v129, v121, v149
	v_fmac_f32_e32 v129, v117, v148
	v_fmac_f32_e32 v129, v118, v150
	v_fmac_f32_e32 v129, v115, v151
	v_add_f32_e32 v128, v128, v129
	v_max_f32_e64 v129, -v128, 0
	v_mul_f32_e64 v128, |v128|, s80
	v_exp_f32_e32 v128, v128
	s_nop 0
	v_add_f32_e32 v128, 1.0, v128
	v_cmp_gt_f32_e32 vcc, s33, v128
	s_nop 1
	v_cndmask_b32_e64 v130, 0, 32, vcc
	v_ldexp_f32 v128, v128, v130
	v_log_f32_e32 v128, v128
	s_nop 0
	v_mul_f32_e32 v130, 0x3f317217, v128
	v_fma_f32 v130, v128, s81, -v130
	v_fmac_f32_e32 v130, 0x3377d1cf, v128
	v_fmac_f32_e32 v130, 0x3f317217, v128
	v_cmp_lt_f32_e64 s[50:51], |v128|, s82
	s_nop 1
	v_cndmask_b32_e64 v128, v128, v130, s[50:51]
	v_cndmask_b32_e32 v130, 0, v217, vcc
	v_sub_f32_e32 v128, v128, v130
	v_add_f32_e32 v128, v129, v128
	v_fmac_f32_e32 v127, 0xbd800000, v128
	ds_write_b32 v57, v127
	ds_read_b128 v[128:131], v58
	ds_read_b128 v[132:135], v58 offset:16
	ds_read_b128 v[136:139], v58 offset:32
	ds_read_b128 v[148:151], v58 offset:48
	s_waitcnt lgkmcnt(3)
	v_mul_f32_e32 v129, v35, v129
	v_fmac_f32_e32 v129, v33, v128
	v_fmac_f32_e32 v129, v34, v130
	v_fmac_f32_e32 v129, v31, v131
	v_add_f32_e32 v128, v126, v129
	s_waitcnt lgkmcnt(2)
	v_mul_f32_e32 v129, v125, v133
	v_fmac_f32_e32 v129, v114, v132
	v_fmac_f32_e32 v129, v124, v134
	v_fmac_f32_e32 v129, v122, v135
	v_add_f32_e32 v128, v128, v129
	s_waitcnt lgkmcnt(1)
	v_mul_f32_e32 v129, v123, v137
	v_fmac_f32_e32 v129, v119, v136
	v_fmac_f32_e32 v129, v120, v138
	v_fmac_f32_e32 v129, v116, v139
	v_add_f32_e32 v128, v128, v129
	s_waitcnt lgkmcnt(0)
	v_mul_f32_e32 v129, v121, v149
	v_fmac_f32_e32 v129, v117, v148
	v_fmac_f32_e32 v129, v118, v150
	v_fmac_f32_e32 v129, v115, v151
	v_add_f32_e32 v128, v128, v129
	v_max_f32_e64 v129, -v128, 0
	v_mul_f32_e64 v128, |v128|, s80
	v_exp_f32_e32 v128, v128
	s_nop 0
	v_add_f32_e32 v128, 1.0, v128
	v_cmp_gt_f32_e32 vcc, s33, v128
	s_nop 1
	v_cndmask_b32_e64 v130, 0, 32, vcc
	v_ldexp_f32 v128, v128, v130
	v_log_f32_e32 v128, v128
	s_nop 0
	v_mul_f32_e32 v130, 0x3f317217, v128
	v_fma_f32 v130, v128, s81, -v130
	v_fmac_f32_e32 v130, 0x3377d1cf, v128
	v_fmac_f32_e32 v130, 0x3f317217, v128
	v_cmp_lt_f32_e64 s[50:51], |v128|, s82
	s_nop 1
	v_cndmask_b32_e64 v128, v128, v130, s[50:51]
	v_cndmask_b32_e32 v130, 0, v217, vcc
	v_sub_f32_e32 v128, v128, v130
	v_add_f32_e32 v128, v129, v128
	v_fmac_f32_e32 v127, 0xbd800000, v128
	ds_write_b32 v59, v127
	ds_read_b128 v[128:131], v60
	ds_read_b128 v[132:135], v60 offset:16
	ds_read_b128 v[136:139], v60 offset:32
	ds_read_b128 v[148:151], v60 offset:48
	s_waitcnt lgkmcnt(3)
	v_mul_f32_e32 v129, v35, v129
	v_fmac_f32_e32 v129, v33, v128
	v_fmac_f32_e32 v129, v34, v130
	v_fmac_f32_e32 v129, v31, v131
	v_add_f32_e32 v128, v126, v129
	s_waitcnt lgkmcnt(2)
	v_mul_f32_e32 v129, v125, v133
	v_fmac_f32_e32 v129, v114, v132
	v_fmac_f32_e32 v129, v124, v134
	v_fmac_f32_e32 v129, v122, v135
	v_add_f32_e32 v128, v128, v129
	s_waitcnt lgkmcnt(1)
	v_mul_f32_e32 v129, v123, v137
	v_fmac_f32_e32 v129, v119, v136
	v_fmac_f32_e32 v129, v120, v138
	v_fmac_f32_e32 v129, v116, v139
	v_add_f32_e32 v128, v128, v129
	s_waitcnt lgkmcnt(0)
	v_mul_f32_e32 v129, v121, v149
	v_fmac_f32_e32 v129, v117, v148
	v_fmac_f32_e32 v129, v118, v150
	v_fmac_f32_e32 v129, v115, v151
	v_add_f32_e32 v128, v128, v129
	v_max_f32_e64 v129, -v128, 0
	v_mul_f32_e64 v128, |v128|, s80
	v_exp_f32_e32 v128, v128
	s_nop 0
	v_add_f32_e32 v128, 1.0, v128
	v_cmp_gt_f32_e32 vcc, s33, v128
	s_nop 1
	v_cndmask_b32_e64 v130, 0, 32, vcc
	v_ldexp_f32 v128, v128, v130
	v_log_f32_e32 v128, v128
	s_nop 0
	v_mul_f32_e32 v130, 0x3f317217, v128
	v_fma_f32 v130, v128, s81, -v130
	v_fmac_f32_e32 v130, 0x3377d1cf, v128
	v_fmac_f32_e32 v130, 0x3f317217, v128
	v_cmp_lt_f32_e64 s[50:51], |v128|, s82
	s_nop 1
	v_cndmask_b32_e64 v128, v128, v130, s[50:51]
	v_cndmask_b32_e32 v130, 0, v217, vcc
	v_sub_f32_e32 v128, v128, v130
	v_add_f32_e32 v128, v129, v128
	v_fmac_f32_e32 v127, 0xbd800000, v128
	ds_write_b32 v61, v127
	ds_read_b128 v[128:131], v62
	ds_read_b128 v[132:135], v62 offset:16
	ds_read_b128 v[136:139], v62 offset:32
	ds_read_b128 v[148:151], v62 offset:48
	s_waitcnt lgkmcnt(3)
	v_mul_f32_e32 v129, v35, v129
	v_fmac_f32_e32 v129, v33, v128
	v_fmac_f32_e32 v129, v34, v130
	v_fmac_f32_e32 v129, v31, v131
	v_add_f32_e32 v128, v126, v129
	s_waitcnt lgkmcnt(2)
	v_mul_f32_e32 v129, v125, v133
	v_fmac_f32_e32 v129, v114, v132
	v_fmac_f32_e32 v129, v124, v134
	v_fmac_f32_e32 v129, v122, v135
	v_add_f32_e32 v128, v128, v129
	s_waitcnt lgkmcnt(1)
	v_mul_f32_e32 v129, v123, v137
	v_fmac_f32_e32 v129, v119, v136
	v_fmac_f32_e32 v129, v120, v138
	v_fmac_f32_e32 v129, v116, v139
	v_add_f32_e32 v128, v128, v129
	s_waitcnt lgkmcnt(0)
	v_mul_f32_e32 v129, v121, v149
	v_fmac_f32_e32 v129, v117, v148
	v_fmac_f32_e32 v129, v118, v150
	v_fmac_f32_e32 v129, v115, v151
	v_add_f32_e32 v128, v128, v129
	v_max_f32_e64 v129, -v128, 0
	v_mul_f32_e64 v128, |v128|, s80
	v_exp_f32_e32 v128, v128
	s_nop 0
	v_add_f32_e32 v128, 1.0, v128
	v_cmp_gt_f32_e32 vcc, s33, v128
	s_nop 1
	v_cndmask_b32_e64 v130, 0, 32, vcc
	v_ldexp_f32 v128, v128, v130
	v_log_f32_e32 v128, v128
	s_nop 0
	v_mul_f32_e32 v130, 0x3f317217, v128
	v_fma_f32 v130, v128, s81, -v130
	v_fmac_f32_e32 v130, 0x3377d1cf, v128
	v_fmac_f32_e32 v130, 0x3f317217, v128
	v_cmp_lt_f32_e64 s[50:51], |v128|, s82
	s_nop 1
	v_cndmask_b32_e64 v128, v128, v130, s[50:51]
	v_cndmask_b32_e32 v130, 0, v217, vcc
	v_sub_f32_e32 v128, v128, v130
	v_add_f32_e32 v128, v129, v128
	v_fmac_f32_e32 v127, 0xbd800000, v128
	ds_write_b32 v63, v127
	ds_read_b128 v[128:131], v64
	ds_read_b128 v[132:135], v64 offset:16
	ds_read_b128 v[136:139], v64 offset:32
	ds_read_b128 v[148:151], v64 offset:48
	s_waitcnt lgkmcnt(3)
	v_mul_f32_e32 v129, v35, v129
	v_fmac_f32_e32 v129, v33, v128
	v_fmac_f32_e32 v129, v34, v130
	v_fmac_f32_e32 v129, v31, v131
	v_add_f32_e32 v128, v126, v129
	s_waitcnt lgkmcnt(2)
	v_mul_f32_e32 v129, v125, v133
	v_fmac_f32_e32 v129, v114, v132
	v_fmac_f32_e32 v129, v124, v134
	v_fmac_f32_e32 v129, v122, v135
	v_add_f32_e32 v128, v128, v129
	s_waitcnt lgkmcnt(1)
	v_mul_f32_e32 v129, v123, v137
	v_fmac_f32_e32 v129, v119, v136
	v_fmac_f32_e32 v129, v120, v138
	v_fmac_f32_e32 v129, v116, v139
	v_add_f32_e32 v128, v128, v129
	s_waitcnt lgkmcnt(0)
	v_mul_f32_e32 v129, v121, v149
	v_fmac_f32_e32 v129, v117, v148
	v_fmac_f32_e32 v129, v118, v150
	v_fmac_f32_e32 v129, v115, v151
	v_add_f32_e32 v128, v128, v129
	v_max_f32_e64 v129, -v128, 0
	v_mul_f32_e64 v128, |v128|, s80
	v_exp_f32_e32 v128, v128
	s_nop 0
	v_add_f32_e32 v128, 1.0, v128
	v_cmp_gt_f32_e32 vcc, s33, v128
	s_nop 1
	v_cndmask_b32_e64 v130, 0, 32, vcc
	v_ldexp_f32 v128, v128, v130
	v_log_f32_e32 v128, v128
	s_nop 0
	v_mul_f32_e32 v130, 0x3f317217, v128
	v_fma_f32 v130, v128, s81, -v130
	v_fmac_f32_e32 v130, 0x3377d1cf, v128
	v_fmac_f32_e32 v130, 0x3f317217, v128
	v_cmp_lt_f32_e64 s[50:51], |v128|, s82
	s_nop 1
	v_cndmask_b32_e64 v128, v128, v130, s[50:51]
	v_cndmask_b32_e32 v130, 0, v217, vcc
	v_sub_f32_e32 v128, v128, v130
	v_add_f32_e32 v128, v129, v128
	v_fmac_f32_e32 v127, 0xbd800000, v128
	ds_write_b32 v65, v127
	ds_read_b128 v[128:131], v66
	ds_read_b128 v[132:135], v66 offset:16
	ds_read_b128 v[136:139], v66 offset:32
	ds_read_b128 v[148:151], v66 offset:48
	s_waitcnt lgkmcnt(3)
	v_mul_f32_e32 v129, v35, v129
	v_fmac_f32_e32 v129, v33, v128
	v_fmac_f32_e32 v129, v34, v130
	v_fmac_f32_e32 v129, v31, v131
	v_add_f32_e32 v128, v126, v129
	s_waitcnt lgkmcnt(2)
	v_mul_f32_e32 v129, v125, v133
	v_fmac_f32_e32 v129, v114, v132
	v_fmac_f32_e32 v129, v124, v134
	v_fmac_f32_e32 v129, v122, v135
	v_add_f32_e32 v128, v128, v129
	s_waitcnt lgkmcnt(1)
	v_mul_f32_e32 v129, v123, v137
	v_fmac_f32_e32 v129, v119, v136
	v_fmac_f32_e32 v129, v120, v138
	v_fmac_f32_e32 v129, v116, v139
	v_add_f32_e32 v128, v128, v129
	s_waitcnt lgkmcnt(0)
	v_mul_f32_e32 v129, v121, v149
	v_fmac_f32_e32 v129, v117, v148
	v_fmac_f32_e32 v129, v118, v150
	v_fmac_f32_e32 v129, v115, v151
	v_add_f32_e32 v128, v128, v129
	v_max_f32_e64 v129, -v128, 0
	v_mul_f32_e64 v128, |v128|, s80
	v_exp_f32_e32 v128, v128
	s_nop 0
	v_add_f32_e32 v128, 1.0, v128
	v_cmp_gt_f32_e32 vcc, s33, v128
	s_nop 1
	v_cndmask_b32_e64 v130, 0, 32, vcc
	v_ldexp_f32 v128, v128, v130
	v_log_f32_e32 v128, v128
	s_nop 0
	v_mul_f32_e32 v130, 0x3f317217, v128
	v_fma_f32 v130, v128, s81, -v130
	v_fmac_f32_e32 v130, 0x3377d1cf, v128
	v_fmac_f32_e32 v130, 0x3f317217, v128
	v_cmp_lt_f32_e64 s[50:51], |v128|, s82
	s_nop 1
	v_cndmask_b32_e64 v128, v128, v130, s[50:51]
	v_cndmask_b32_e32 v130, 0, v217, vcc
	v_sub_f32_e32 v128, v128, v130
	v_add_f32_e32 v128, v129, v128
	v_fmac_f32_e32 v127, 0xbd800000, v128
	ds_write_b32 v67, v127
	ds_read_b128 v[128:131], v68
	ds_read_b128 v[132:135], v68 offset:16
	ds_read_b128 v[136:139], v68 offset:32
	ds_read_b128 v[148:151], v68 offset:48
	s_waitcnt lgkmcnt(3)
	v_mul_f32_e32 v129, v35, v129
	v_fmac_f32_e32 v129, v33, v128
	v_fmac_f32_e32 v129, v34, v130
	v_fmac_f32_e32 v129, v31, v131
	v_add_f32_e32 v128, v126, v129
	s_waitcnt lgkmcnt(2)
	v_mul_f32_e32 v129, v125, v133
	v_fmac_f32_e32 v129, v114, v132
	v_fmac_f32_e32 v129, v124, v134
	v_fmac_f32_e32 v129, v122, v135
	v_add_f32_e32 v128, v128, v129
	s_waitcnt lgkmcnt(1)
	v_mul_f32_e32 v129, v123, v137
	v_fmac_f32_e32 v129, v119, v136
	v_fmac_f32_e32 v129, v120, v138
	v_fmac_f32_e32 v129, v116, v139
	v_add_f32_e32 v128, v128, v129
	s_waitcnt lgkmcnt(0)
	v_mul_f32_e32 v129, v121, v149
	v_fmac_f32_e32 v129, v117, v148
	v_fmac_f32_e32 v129, v118, v150
	v_fmac_f32_e32 v129, v115, v151
	v_add_f32_e32 v128, v128, v129
	v_max_f32_e64 v129, -v128, 0
	v_mul_f32_e64 v128, |v128|, s80
	v_exp_f32_e32 v128, v128
	s_nop 0
	v_add_f32_e32 v128, 1.0, v128
	v_cmp_gt_f32_e32 vcc, s33, v128
	s_nop 1
	v_cndmask_b32_e64 v130, 0, 32, vcc
	v_ldexp_f32 v128, v128, v130
	v_log_f32_e32 v128, v128
	s_nop 0
	v_mul_f32_e32 v130, 0x3f317217, v128
	v_fma_f32 v130, v128, s81, -v130
	v_fmac_f32_e32 v130, 0x3377d1cf, v128
	v_fmac_f32_e32 v130, 0x3f317217, v128
	v_cmp_lt_f32_e64 s[50:51], |v128|, s82
	s_nop 1
	v_cndmask_b32_e64 v128, v128, v130, s[50:51]
	v_cndmask_b32_e32 v130, 0, v217, vcc
	v_sub_f32_e32 v128, v128, v130
	v_add_f32_e32 v128, v129, v128
	v_fmac_f32_e32 v127, 0xbd800000, v128
	ds_write_b32 v69, v127
	ds_read_b128 v[128:131], v70
	ds_read_b128 v[132:135], v70 offset:16
	ds_read_b128 v[136:139], v70 offset:32
	ds_read_b128 v[148:151], v70 offset:48
	s_waitcnt lgkmcnt(3)
	v_mul_f32_e32 v129, v35, v129
	v_fmac_f32_e32 v129, v33, v128
	v_fmac_f32_e32 v129, v34, v130
	v_fmac_f32_e32 v129, v31, v131
	v_add_f32_e32 v128, v126, v129
	s_waitcnt lgkmcnt(2)
	v_mul_f32_e32 v129, v125, v133
	v_fmac_f32_e32 v129, v114, v132
	v_fmac_f32_e32 v129, v124, v134
	v_fmac_f32_e32 v129, v122, v135
	v_add_f32_e32 v128, v128, v129
	s_waitcnt lgkmcnt(1)
	v_mul_f32_e32 v129, v123, v137
	v_fmac_f32_e32 v129, v119, v136
	v_fmac_f32_e32 v129, v120, v138
	v_fmac_f32_e32 v129, v116, v139
	v_add_f32_e32 v128, v128, v129
	s_waitcnt lgkmcnt(0)
	v_mul_f32_e32 v129, v121, v149
	v_fmac_f32_e32 v129, v117, v148
	v_fmac_f32_e32 v129, v118, v150
	v_fmac_f32_e32 v129, v115, v151
	v_add_f32_e32 v128, v128, v129
	v_max_f32_e64 v129, -v128, 0
	v_mul_f32_e64 v128, |v128|, s80
	v_exp_f32_e32 v128, v128
	s_nop 0
	v_add_f32_e32 v128, 1.0, v128
	v_cmp_gt_f32_e32 vcc, s33, v128
	s_nop 1
	v_cndmask_b32_e64 v130, 0, 32, vcc
	v_ldexp_f32 v128, v128, v130
	v_log_f32_e32 v128, v128
	s_nop 0
	v_mul_f32_e32 v130, 0x3f317217, v128
	v_fma_f32 v130, v128, s81, -v130
	v_fmac_f32_e32 v130, 0x3377d1cf, v128
	v_fmac_f32_e32 v130, 0x3f317217, v128
	v_cmp_lt_f32_e64 s[50:51], |v128|, s82
	s_nop 1
	v_cndmask_b32_e64 v128, v128, v130, s[50:51]
	v_cndmask_b32_e32 v130, 0, v217, vcc
	v_sub_f32_e32 v128, v128, v130
	v_add_f32_e32 v128, v129, v128
	v_fmac_f32_e32 v127, 0xbd800000, v128
	ds_write_b32 v71, v127
	ds_read_b128 v[128:131], v72
	ds_read_b128 v[132:135], v72 offset:16
	ds_read_b128 v[136:139], v72 offset:32
	ds_read_b128 v[148:151], v72 offset:48
	s_waitcnt lgkmcnt(3)
	v_mul_f32_e32 v129, v35, v129
	v_fmac_f32_e32 v129, v33, v128
	v_fmac_f32_e32 v129, v34, v130
	v_fmac_f32_e32 v129, v31, v131
	v_add_f32_e32 v128, v126, v129
	s_waitcnt lgkmcnt(2)
	v_mul_f32_e32 v129, v125, v133
	v_fmac_f32_e32 v129, v114, v132
	v_fmac_f32_e32 v129, v124, v134
	v_fmac_f32_e32 v129, v122, v135
	v_add_f32_e32 v128, v128, v129
	s_waitcnt lgkmcnt(1)
	v_mul_f32_e32 v129, v123, v137
	v_fmac_f32_e32 v129, v119, v136
	v_fmac_f32_e32 v129, v120, v138
	v_fmac_f32_e32 v129, v116, v139
	v_add_f32_e32 v128, v128, v129
	s_waitcnt lgkmcnt(0)
	v_mul_f32_e32 v129, v121, v149
	v_fmac_f32_e32 v129, v117, v148
	v_fmac_f32_e32 v129, v118, v150
	v_fmac_f32_e32 v129, v115, v151
	v_add_f32_e32 v128, v128, v129
	v_max_f32_e64 v129, -v128, 0
	v_mul_f32_e64 v128, |v128|, s80
	v_exp_f32_e32 v128, v128
	s_nop 0
	v_add_f32_e32 v128, 1.0, v128
	v_cmp_gt_f32_e32 vcc, s33, v128
	s_nop 1
	v_cndmask_b32_e64 v130, 0, 32, vcc
	v_ldexp_f32 v128, v128, v130
	v_log_f32_e32 v128, v128
	s_nop 0
	v_mul_f32_e32 v130, 0x3f317217, v128
	v_fma_f32 v130, v128, s81, -v130
	v_fmac_f32_e32 v130, 0x3377d1cf, v128
	v_fmac_f32_e32 v130, 0x3f317217, v128
	v_cmp_lt_f32_e64 s[50:51], |v128|, s82
	s_nop 1
	v_cndmask_b32_e64 v128, v128, v130, s[50:51]
	v_cndmask_b32_e32 v130, 0, v217, vcc
	v_sub_f32_e32 v128, v128, v130
	v_add_f32_e32 v128, v129, v128
	v_fmac_f32_e32 v127, 0xbd800000, v128
	ds_write_b32 v73, v127
	ds_read_b128 v[128:131], v74
	ds_read_b128 v[132:135], v74 offset:16
	ds_read_b128 v[136:139], v74 offset:32
	ds_read_b128 v[148:151], v74 offset:48
	s_waitcnt lgkmcnt(3)
	v_mul_f32_e32 v129, v35, v129
	v_fmac_f32_e32 v129, v33, v128
	v_fmac_f32_e32 v129, v34, v130
	v_fmac_f32_e32 v129, v31, v131
	v_add_f32_e32 v128, v126, v129
	s_waitcnt lgkmcnt(2)
	v_mul_f32_e32 v129, v125, v133
	v_fmac_f32_e32 v129, v114, v132
	v_fmac_f32_e32 v129, v124, v134
	v_fmac_f32_e32 v129, v122, v135
	v_add_f32_e32 v128, v128, v129
	s_waitcnt lgkmcnt(1)
	v_mul_f32_e32 v129, v123, v137
	v_fmac_f32_e32 v129, v119, v136
	v_fmac_f32_e32 v129, v120, v138
	v_fmac_f32_e32 v129, v116, v139
	v_add_f32_e32 v128, v128, v129
	s_waitcnt lgkmcnt(0)
	v_mul_f32_e32 v129, v121, v149
	v_fmac_f32_e32 v129, v117, v148
	v_fmac_f32_e32 v129, v118, v150
	v_fmac_f32_e32 v129, v115, v151
	v_add_f32_e32 v128, v128, v129
	v_max_f32_e64 v129, -v128, 0
	v_mul_f32_e64 v128, |v128|, s80
	v_exp_f32_e32 v128, v128
	s_nop 0
	v_add_f32_e32 v128, 1.0, v128
	v_cmp_gt_f32_e32 vcc, s33, v128
	s_nop 1
	v_cndmask_b32_e64 v130, 0, 32, vcc
	v_ldexp_f32 v128, v128, v130
	v_log_f32_e32 v128, v128
	s_nop 0
	v_mul_f32_e32 v130, 0x3f317217, v128
	v_fma_f32 v130, v128, s81, -v130
	v_fmac_f32_e32 v130, 0x3377d1cf, v128
	v_fmac_f32_e32 v130, 0x3f317217, v128
	v_cmp_lt_f32_e64 s[50:51], |v128|, s82
	s_nop 1
	v_cndmask_b32_e64 v128, v128, v130, s[50:51]
	v_cndmask_b32_e32 v130, 0, v217, vcc
	v_sub_f32_e32 v128, v128, v130
	v_add_f32_e32 v128, v129, v128
	v_fmac_f32_e32 v127, 0xbd800000, v128
	ds_write_b32 v75, v127
	ds_read_b128 v[128:131], v76
	ds_read_b128 v[132:135], v76 offset:16
	ds_read_b128 v[136:139], v76 offset:32
	ds_read_b128 v[148:151], v76 offset:48
	s_waitcnt lgkmcnt(3)
	v_mul_f32_e32 v129, v35, v129
	v_fmac_f32_e32 v129, v33, v128
	v_fmac_f32_e32 v129, v34, v130
	v_fmac_f32_e32 v129, v31, v131
	v_add_f32_e32 v128, v126, v129
	s_waitcnt lgkmcnt(2)
	v_mul_f32_e32 v129, v125, v133
	v_fmac_f32_e32 v129, v114, v132
	v_fmac_f32_e32 v129, v124, v134
	v_fmac_f32_e32 v129, v122, v135
	v_add_f32_e32 v128, v128, v129
	s_waitcnt lgkmcnt(1)
	v_mul_f32_e32 v129, v123, v137
	v_fmac_f32_e32 v129, v119, v136
	v_fmac_f32_e32 v129, v120, v138
	v_fmac_f32_e32 v129, v116, v139
	v_add_f32_e32 v128, v128, v129
	s_waitcnt lgkmcnt(0)
	v_mul_f32_e32 v129, v121, v149
	v_fmac_f32_e32 v129, v117, v148
	v_fmac_f32_e32 v129, v118, v150
	v_fmac_f32_e32 v129, v115, v151
	v_add_f32_e32 v128, v128, v129
	v_max_f32_e64 v129, -v128, 0
	v_mul_f32_e64 v128, |v128|, s80
	v_exp_f32_e32 v128, v128
	s_nop 0
	v_add_f32_e32 v128, 1.0, v128
	v_cmp_gt_f32_e32 vcc, s33, v128
	s_nop 1
	v_cndmask_b32_e64 v130, 0, 32, vcc
	v_ldexp_f32 v128, v128, v130
	v_log_f32_e32 v128, v128
	s_nop 0
	v_mul_f32_e32 v130, 0x3f317217, v128
	v_fma_f32 v130, v128, s81, -v130
	v_fmac_f32_e32 v130, 0x3377d1cf, v128
	v_fmac_f32_e32 v130, 0x3f317217, v128
	v_cmp_lt_f32_e64 s[50:51], |v128|, s82
	s_nop 1
	v_cndmask_b32_e64 v128, v128, v130, s[50:51]
	v_cndmask_b32_e32 v130, 0, v217, vcc
	v_sub_f32_e32 v128, v128, v130
	v_add_f32_e32 v128, v129, v128
	v_fmac_f32_e32 v127, 0xbd800000, v128
	ds_write_b32 v77, v127
	ds_read_b128 v[128:131], v78
	ds_read_b128 v[132:135], v78 offset:16
	ds_read_b128 v[136:139], v78 offset:32
	ds_read_b128 v[148:151], v78 offset:48
	s_waitcnt lgkmcnt(3)
	v_mul_f32_e32 v129, v35, v129
	v_fmac_f32_e32 v129, v33, v128
	v_fmac_f32_e32 v129, v34, v130
	v_fmac_f32_e32 v129, v31, v131
	v_add_f32_e32 v128, v126, v129
	s_waitcnt lgkmcnt(2)
	v_mul_f32_e32 v129, v125, v133
	v_fmac_f32_e32 v129, v114, v132
	v_fmac_f32_e32 v129, v124, v134
	v_fmac_f32_e32 v129, v122, v135
	v_add_f32_e32 v128, v128, v129
	s_waitcnt lgkmcnt(1)
	v_mul_f32_e32 v129, v123, v137
	v_fmac_f32_e32 v129, v119, v136
	v_fmac_f32_e32 v129, v120, v138
	v_fmac_f32_e32 v129, v116, v139
	v_add_f32_e32 v128, v128, v129
	s_waitcnt lgkmcnt(0)
	v_mul_f32_e32 v129, v121, v149
	v_fmac_f32_e32 v129, v117, v148
	v_fmac_f32_e32 v129, v118, v150
	v_fmac_f32_e32 v129, v115, v151
	v_add_f32_e32 v128, v128, v129
	v_max_f32_e64 v129, -v128, 0
	v_mul_f32_e64 v128, |v128|, s80
	v_exp_f32_e32 v128, v128
	s_nop 0
	v_add_f32_e32 v128, 1.0, v128
	v_cmp_gt_f32_e32 vcc, s33, v128
	s_nop 1
	v_cndmask_b32_e64 v130, 0, 32, vcc
	v_ldexp_f32 v128, v128, v130
	v_log_f32_e32 v128, v128
	s_nop 0
	v_mul_f32_e32 v130, 0x3f317217, v128
	v_fma_f32 v130, v128, s81, -v130
	v_fmac_f32_e32 v130, 0x3377d1cf, v128
	v_fmac_f32_e32 v130, 0x3f317217, v128
	v_cmp_lt_f32_e64 s[50:51], |v128|, s82
	s_nop 1
	v_cndmask_b32_e64 v128, v128, v130, s[50:51]
	v_cndmask_b32_e32 v130, 0, v217, vcc
	v_sub_f32_e32 v128, v128, v130
	v_add_f32_e32 v128, v129, v128
	v_fmac_f32_e32 v127, 0xbd800000, v128
	ds_write_b32 v79, v127
	ds_read_b128 v[128:131], v80
	ds_read_b128 v[132:135], v80 offset:16
	ds_read_b128 v[136:139], v80 offset:32
	ds_read_b128 v[148:151], v80 offset:48
	s_waitcnt lgkmcnt(3)
	v_mul_f32_e32 v35, v35, v129
	v_fmac_f32_e32 v35, v33, v128
	s_waitcnt lgkmcnt(2)
	v_mul_f32_e32 v33, v125, v133
	v_fmac_f32_e32 v35, v34, v130
	v_fmac_f32_e32 v33, v114, v132
	v_fmac_f32_e32 v35, v31, v131
	v_fmac_f32_e32 v33, v124, v134
	v_add_f32_e32 v31, v126, v35
	v_fmac_f32_e32 v33, v122, v135
	v_add_f32_e32 v31, v31, v33
	s_waitcnt lgkmcnt(1)
	v_mul_f32_e32 v33, v123, v137
	v_fmac_f32_e32 v33, v119, v136
	v_fmac_f32_e32 v33, v120, v138
	v_fmac_f32_e32 v33, v116, v139
	v_add_f32_e32 v31, v31, v33
	s_waitcnt lgkmcnt(0)
	v_mul_f32_e32 v33, v121, v149
	v_fmac_f32_e32 v33, v117, v148
	v_fmac_f32_e32 v33, v118, v150
	v_fmac_f32_e32 v33, v115, v151
	v_add_f32_e32 v31, v31, v33
	v_max_f32_e64 v33, -v31, 0
	v_mul_f32_e64 v31, |v31|, s80
	v_exp_f32_e32 v31, v31
	v_add_u32_e32 v114, v40, v45
	v_add_f32_e32 v31, 1.0, v31
	v_cmp_gt_f32_e32 vcc, s33, v31
	s_nop 1
	v_cndmask_b32_e64 v34, 0, 32, vcc
	v_ldexp_f32 v31, v31, v34
	v_log_f32_e32 v31, v31
	s_nop 0
	v_mul_f32_e32 v34, 0x3f317217, v31
	v_fma_f32 v34, v31, s81, -v34
	v_fmac_f32_e32 v34, 0x3377d1cf, v31
	v_fmac_f32_e32 v34, 0x3f317217, v31
	v_cmp_lt_f32_e64 s[50:51], |v31|, s82
	s_nop 1
	v_cndmask_b32_e64 v31, v31, v34, s[50:51]
	v_cndmask_b32_e32 v34, 0, v217, vcc
	v_sub_f32_e32 v31, v31, v34
	v_add_f32_e32 v31, v33, v31
	v_fmac_f32_e32 v127, 0xbd800000, v31
	ds_write_b32 v81, v127
	ds_write_b32 v46, v127
	s_waitcnt lgkmcnt(0)
	s_barrier
	ds_read2st64_b32 v[34:35], v114 offset1:1
	s_and_saveexec_b64 s[40:41], s[0:1]
	s_xor_b64 s[40:41], exec, s[40:41]
	s_and_b64 s[26:27], s[42:43], exec
	s_or_saveexec_b64 s[40:41], s[40:41]
	s_waitcnt lgkmcnt(0)
	v_add_f32_e32 v31, 0, v34
	v_cndmask_b32_e64 v33, v31, 0, s[2:3]
	v_mov_b32_e32 v115, v33
	s_xor_b64 exec, exec, s[40:41]
	s_andn2_b64 s[26:27], s[26:27], exec
	s_and_b64 s[50:51], s[38:39], exec
	v_mov_b32_e32 v115, 0
	s_or_b64 s[26:27], s[26:27], s[50:51]
	s_or_b64 exec, exec, s[40:41]
	s_and_saveexec_b64 s[40:41], s[26:27]
	v_add_f32_e32 v115, v35, v33
	s_or_b64 exec, exec, s[40:41]
	ds_read_b32 v33, v114 offset:512
	s_mov_b64 s[26:27], 0
	s_and_saveexec_b64 s[40:41], s[0:1]
	s_xor_b64 s[40:41], exec, s[40:41]
	s_cbranch_execz .LBB0_236
	s_and_b64 s[26:27], s[44:45], exec
	s_andn2_saveexec_b64 s[40:41], s[40:41]
	s_cbranch_execnz .LBB0_237
